# light flat barriers (8 sharded arrival counters, no L2 writeback, thread-0 poll + buffer_inv) after P5, P6, P7, P9 whose outputs are all drained write-through stores
# baseline (speedup 1.0000x reference)
.LBB0_809:
	s_waitcnt vmcnt(0)
	s_barrier
	s_and_saveexec_b64 s[0:1], s[56:57]
	s_cbranch_execz .LBB0_861
	s_and_b32 s3, s2, 7
	s_lshl_b32 s3, s3, 7
	s_add_u32 s4, s28, 0x3880
	s_addc_u32 s5, s29, 0
	v_mov_b32_e32 v0, s3
	v_mov_b32_e32 v1, 1
	v_mov_b32_e32 v2, 0
	s_waitcnt vmcnt(0) lgkmcnt(0)
	global_atomic_add v0, v1, s[4:5]
.Llb6_poll:
	global_load_dword v3, v2, s[4:5] sc1
	global_load_dword v4, v2, s[4:5] offset:128 sc1
	global_load_dword v5, v2, s[4:5] offset:256 sc1
	global_load_dword v6, v2, s[4:5] offset:384 sc1
	global_load_dword v7, v2, s[4:5] offset:512 sc1
	global_load_dword v8, v2, s[4:5] offset:640 sc1
	global_load_dword v9, v2, s[4:5] offset:768 sc1
	global_load_dword v10, v2, s[4:5] offset:896 sc1
	s_waitcnt vmcnt(0)
	v_min_u32_e32 v3, v3, v4
	v_min_u32_e32 v5, v5, v6
	v_min_u32_e32 v7, v7, v8
	v_min_u32_e32 v9, v9, v10
	v_min_u32_e32 v3, v3, v5
	v_min_u32_e32 v7, v7, v9
	v_min_u32_e32 v3, v3, v7
	v_cmp_gt_u32_e32 vcc, 0x20, v3
	s_cbranch_vccz .Llb6_go
	s_sleep 1
	s_branch .Llb6_poll
.Llb6_go:
	buffer_inv sc1
	s_waitcnt vmcnt(0)

.LBB0_877:
	s_andn2_b64 vcc, exec, s[52:53]
	s_cbranch_vccnz .LBB0_879
	global_store_dwordx4 v[8:9], v[0:3], off sc1

.LBB0_933:
	s_andn2_b64 vcc, exec, s[52:53]
	s_cbranch_vccnz .LBB0_935
	global_store_dwordx4 v[4:5], v[0:3], off sc1

.LBB0_939:
	global_store_dwordx4 v[4:5], v[0:3], off sc1
	s_andn2_b64 vcc, exec, s[4:5]
	s_mov_b64 s[4:5], -1
	s_cbranch_vccnz .LBB0_868

.LBB0_943:
	s_waitcnt vmcnt(0)
	s_waitcnt vmcnt(0)
	s_barrier
	s_and_saveexec_b64 s[0:1], s[56:57]
	s_cbranch_execz .LBB0_995
	s_and_b32 s3, s2, 7
	s_lshl_b32 s3, s3, 7
	s_add_u32 s4, s28, 0x3880
	s_addc_u32 s5, s29, 0
	v_mov_b32_e32 v0, s3
	v_mov_b32_e32 v1, 1
	v_mov_b32_e32 v2, 0
	s_waitcnt vmcnt(0) lgkmcnt(0)
	global_atomic_add v0, v1, s[4:5]
.Llb7_poll:
	global_load_dword v3, v2, s[4:5] sc1
	global_load_dword v4, v2, s[4:5] offset:128 sc1
	global_load_dword v5, v2, s[4:5] offset:256 sc1
	global_load_dword v6, v2, s[4:5] offset:384 sc1
	global_load_dword v7, v2, s[4:5] offset:512 sc1
	global_load_dword v8, v2, s[4:5] offset:640 sc1
	global_load_dword v9, v2, s[4:5] offset:768 sc1
	global_load_dword v10, v2, s[4:5] offset:896 sc1
	s_waitcnt vmcnt(0)
	v_min_u32_e32 v3, v3, v4
	v_min_u32_e32 v5, v5, v6
	v_min_u32_e32 v7, v7, v8
	v_min_u32_e32 v9, v9, v10
	v_min_u32_e32 v3, v3, v5
	v_min_u32_e32 v7, v7, v9
	v_min_u32_e32 v3, v3, v7
	v_cmp_gt_u32_e32 vcc, 0x40, v3
	s_cbranch_vccz .Llb7_go
	s_sleep 1
	s_branch .Llb7_poll

.Llb8_poll:
	global_load_dword v3, v2, s[4:5] sc1
	global_load_dword v4, v2, s[4:5] offset:128 sc1
	global_load_dword v5, v2, s[4:5] offset:256 sc1
	global_load_dword v6, v2, s[4:5] offset:384 sc1
	global_load_dword v7, v2, s[4:5] offset:512 sc1
	global_load_dword v8, v2, s[4:5] offset:640 sc1
	global_load_dword v9, v2, s[4:5] offset:768 sc1
	global_load_dword v10, v2, s[4:5] offset:896 sc1
	s_waitcnt vmcnt(0)
	v_min_u32_e32 v3, v3, v4
	v_min_u32_e32 v5, v5, v6
	v_min_u32_e32 v7, v7, v8
	v_min_u32_e32 v9, v9, v10
	v_min_u32_e32 v3, v3, v5
	v_min_u32_e32 v7, v7, v9
	v_min_u32_e32 v3, v3, v7
	v_cmp_gt_u32_e32 vcc, 0x60, v3
	s_cbranch_vccz .Llb8_go
	s_sleep 1
	s_branch .Llb8_poll

.LBB0_1200:
	s_andn2_b64 vcc, exec, s[44:45]
	s_cbranch_vccnz .LBB0_1202
	global_store_dwordx4 v[8:9], v[0:3], off sc1

.LBB0_1256:
	s_andn2_b64 vcc, exec, s[44:45]
	s_cbranch_vccnz .LBB0_1258
	global_store_dwordx4 v[4:5], v[0:3], off sc1

.LBB0_1262:
	global_store_dwordx4 v[4:5], v[0:3], off sc1
	s_andn2_b64 vcc, exec, s[0:1]
	s_mov_b64 s[0:1], -1
	s_cbranch_vccnz .LBB0_1191

.LBB0_1266:
	s_waitcnt vmcnt(0)
	s_waitcnt vmcnt(0)
	s_barrier
	s_and_saveexec_b64 s[0:1], s[56:57]
	s_cbranch_execz .LBB0_1318
	s_lshr_b32 s3, s76, 3
	s_and_b32 s3, s3, 7
	s_lshl_b32 s3, s3, 7
	s_add_u32 s4, s28, 0x3880
	s_addc_u32 s5, s29, 0
	v_mov_b32_e32 v0, s3
	v_mov_b32_e32 v1, 1
	v_mov_b32_e32 v2, 0
	s_waitcnt vmcnt(0) lgkmcnt(0)
	global_atomic_add v0, v1, s[4:5]
.Llb10_poll:
	global_load_dword v3, v2, s[4:5] sc1
	global_load_dword v4, v2, s[4:5] offset:128 sc1
	global_load_dword v5, v2, s[4:5] offset:256 sc1
	global_load_dword v6, v2, s[4:5] offset:384 sc1
	global_load_dword v7, v2, s[4:5] offset:512 sc1
	global_load_dword v8, v2, s[4:5] offset:640 sc1
	global_load_dword v9, v2, s[4:5] offset:768 sc1
	global_load_dword v10, v2, s[4:5] offset:896 sc1
	s_waitcnt vmcnt(0)
	v_min_u32_e32 v3, v3, v4
	v_min_u32_e32 v5, v5, v6
	v_min_u32_e32 v7, v7, v8
	v_min_u32_e32 v9, v9, v10
	v_min_u32_e32 v3, v3, v5
	v_min_u32_e32 v7, v7, v9
	v_min_u32_e32 v3, v3, v7
	v_cmp_gt_u32_e32 vcc, 0x80, v3
	s_cbranch_vccz .Llb10_go
	s_sleep 1
	s_branch .Llb10_poll
